# v51 + FFN-up halo publish reads the weight-row scales from the prefetched LDS copy (no global loads, no vmcnt(0) round trips)
# baseline (speedup 1.0000x reference)
.LBB0_1372:
	s_or_b64 exec, exec, s[4:5]
	s_lshl_b32 s4, s42, 7
	v_lshlrev_b32_e32 v204, 3, v239
	s_or_b32 s4, s4, s76
	v_cvt_f32_i32_e32 v195, v119
	v_cvt_f32_i32_e32 v194, v118
	v_cvt_f32_i32_e32 v193, v121
	v_cvt_f32_i32_e32 v192, v120
	v_cvt_f32_i32_e32 v191, v115
	v_cvt_f32_i32_e32 v190, v114
	v_cvt_f32_i32_e32 v189, v117
	v_cvt_f32_i32_e32 v188, v116
	v_add_u32_e32 v186, s4, v204
	s_lshl_b32 s42, s42, 8
	s_lshl_b32 s31, s40, 1
	v_ashrrev_i32_e32 v187, 31, v186
	v_or_b32_e32 v122, s41, v222
	s_ashr_i32 s43, s42, 31
	v_ashrrev_i32_e32 v205, 31, v204
	v_cmp_eq_u32_e64 s[4:5], 0, v122
	s_mul_hi_i32 s35, s31, 0x1c000
	s_mul_i32 s56, s31, 0x1c000
	v_lshlrev_b64 v[114:115], 2, v[186:187]
	s_mul_i32 vcc_lo, s9, 0x1400
	v_add_u32_e32 v252, s76, v204
	v_lshl_add_u32 v252, v252, 2, vcc_lo
	v_add_u32_e32 v252, 0x22c00, v252
	s_and_saveexec_b64 s[18:19], s[4:5]
	s_cbranch_execz .LBB0_1374
	s_lshl_b64 vcc, s[42:43], 2
	s_add_u32 vcc_lo, s94, vcc_lo
	s_addc_u32 vcc_hi, s95, vcc_hi
	v_lshl_add_u64 v[124:125], v[204:205], 2, vcc
	ds_read_b128 v[244:247], v252 offset:4096
	s_add_u32 vcc_lo, s69, s56
	v_pk_mul_f32 v[120:121], v[162:163], v[192:193] op_sel_hi:[0,1]
	v_pk_mul_f32 v[122:123], v[162:163], v[194:195] op_sel_hi:[0,1]
	s_addc_u32 vcc_hi, s70, s35
	s_or_b32 s57, s31, 1
	s_mul_hi_i32 s79, s57, 0x1c000
	s_mul_i32 s57, s57, 0x1c000
	s_waitcnt lgkmcnt(0)
	v_pk_mul_f32 v[116:117], v[122:123], v[244:245]
	v_pk_mul_f32 v[118:119], v[120:121], v[246:247]
	v_lshl_add_u64 v[120:121], vcc, 0, v[114:115]
	global_store_dwordx4 v[120:121], v[116:119], off
	s_add_u32 vcc_lo, s69, s57
	v_pk_mul_f32 v[120:121], v[162:163], v[188:189] op_sel:[1,0]
	v_pk_mul_f32 v[122:123], v[162:163], v[190:191] op_sel:[1,0]
	s_addc_u32 vcc_hi, s70, s79
	v_pk_mul_f32 v[116:117], v[122:123], v[244:245]
	v_pk_mul_f32 v[118:119], v[120:121], v[246:247]
	v_lshl_add_u64 v[120:121], vcc, 0, v[114:115]
	global_store_dwordx4 v[120:121], v[116:119], off

.LBB0_1376:
	s_or_b64 exec, exec, s[18:19]
	v_cvt_f32_i32_e32 v121, v103
	v_cvt_f32_i32_e32 v120, v102
	v_cvt_f32_i32_e32 v125, v105
	v_cvt_f32_i32_e32 v124, v104
	v_cvt_f32_i32_e32 v119, v99
	v_cvt_f32_i32_e32 v118, v98
	v_cvt_f32_i32_e32 v123, v101
	v_cvt_f32_i32_e32 v122, v100
	s_and_saveexec_b64 s[18:19], s[4:5]
	s_cbranch_execz .LBB0_1378
	s_lshl_b64 vcc, s[42:43], 2
	s_add_u32 vcc_lo, s94, vcc_lo
	s_addc_u32 vcc_hi, s95, vcc_hi
	v_lshl_add_u64 v[108:109], v[204:205], 2, vcc
	ds_read_b128 v[244:247], v252 offset:4112
	s_add_u32 vcc_lo, s69, s56
	v_pk_mul_f32 v[102:103], v[162:163], v[124:125] op_sel_hi:[0,1]
	v_pk_mul_f32 v[104:105], v[162:163], v[120:121] op_sel_hi:[0,1]
	s_addc_u32 vcc_hi, s70, s35
	s_or_b32 s57, s31, 1
	s_mul_hi_i32 s79, s57, 0x1c000
	s_mul_i32 s57, s57, 0x1c000
	s_waitcnt lgkmcnt(0)
	v_pk_mul_f32 v[98:99], v[104:105], v[244:245]
	v_pk_mul_f32 v[100:101], v[102:103], v[246:247]
	v_lshl_add_u64 v[102:103], vcc, 0, v[114:115]
	global_store_dwordx4 v[102:103], v[98:101], off offset:16
	s_add_u32 vcc_lo, s69, s57
	v_pk_mul_f32 v[102:103], v[162:163], v[122:123] op_sel:[1,0]
	v_pk_mul_f32 v[104:105], v[162:163], v[118:119] op_sel:[1,0]
	s_addc_u32 vcc_hi, s70, s79
	v_pk_mul_f32 v[98:99], v[104:105], v[244:245]
	v_pk_mul_f32 v[100:101], v[102:103], v[246:247]
	v_lshl_add_u64 v[102:103], vcc, 0, v[114:115]
	global_store_dwordx4 v[102:103], v[98:101], off offset:16

.LBB0_1380:
	s_or_b64 exec, exec, s[18:19]
	v_cvt_f32_i32_e32 v221, v87
	v_cvt_f32_i32_e32 v220, v86
	v_cvt_f32_i32_e32 v219, v89
	v_cvt_f32_i32_e32 v218, v88
	v_cvt_f32_i32_e32 v217, v83
	v_cvt_f32_i32_e32 v216, v82
	v_cvt_f32_i32_e32 v215, v85
	v_cvt_f32_i32_e32 v214, v84
	s_and_saveexec_b64 s[18:19], s[4:5]
	s_cbranch_execz .LBB0_1382
	s_lshl_b64 vcc, s[42:43], 2
	s_add_u32 vcc_lo, s94, vcc_lo
	s_addc_u32 vcc_hi, s95, vcc_hi
	v_lshl_add_u64 v[90:91], v[204:205], 2, vcc
	ds_read_b128 v[244:247], v252 offset:4608
	s_add_u32 vcc_lo, s69, s56
	v_pk_mul_f32 v[86:87], v[162:163], v[218:219] op_sel_hi:[0,1]
	s_addc_u32 vcc_hi, s70, s35
	v_pk_mul_f32 v[88:89], v[162:163], v[220:221] op_sel_hi:[0,1]
	s_or_b32 s57, s31, 1
	s_mul_hi_i32 s79, s57, 0x1c000
	s_mul_i32 s57, s57, 0x1c000
	s_waitcnt lgkmcnt(0)
	v_pk_mul_f32 v[84:85], v[86:87], v[246:247]
	v_lshl_add_u64 v[86:87], vcc, 0, v[114:115]
	v_add_co_u32_e32 v86, vcc, s1, v86
	v_pk_mul_f32 v[82:83], v[88:89], v[244:245]
	s_nop 0
	v_addc_co_u32_e32 v87, vcc, 0, v87, vcc
	global_store_dwordx4 v[86:87], v[82:85], off
	s_add_u32 vcc_lo, s69, s57
	v_pk_mul_f32 v[86:87], v[162:163], v[214:215] op_sel:[1,0]
	s_addc_u32 vcc_hi, s70, s79
	v_pk_mul_f32 v[88:89], v[162:163], v[216:217] op_sel:[1,0]
	v_pk_mul_f32 v[84:85], v[86:87], v[246:247]
	v_lshl_add_u64 v[86:87], vcc, 0, v[114:115]
	v_add_co_u32_e32 v86, vcc, 0xe000, v86
	v_pk_mul_f32 v[82:83], v[88:89], v[244:245]
	s_nop 0
	v_addc_co_u32_e32 v87, vcc, 0, v87, vcc
	global_store_dwordx4 v[86:87], v[82:85], off

.LBB0_1384:
	s_or_b64 exec, exec, s[18:19]
	v_cvt_f32_i32_e32 v181, v71
	v_cvt_f32_i32_e32 v180, v70
	v_cvt_f32_i32_e32 v185, v73
	v_cvt_f32_i32_e32 v184, v72
	v_cvt_f32_i32_e32 v179, v67
	v_cvt_f32_i32_e32 v178, v66
	v_cvt_f32_i32_e32 v183, v69
	v_cvt_f32_i32_e32 v182, v68
	s_and_saveexec_b64 s[18:19], s[4:5]
	s_cbranch_execz .LBB0_1386
	s_lshl_b64 s[4:5], s[42:43], 2
	s_add_u32 s4, s94, s4
	s_addc_u32 s5, s95, s5
	v_lshl_add_u64 v[74:75], v[204:205], 2, s[4:5]
	ds_read_b128 v[244:247], v252 offset:4624
	s_add_u32 s4, s69, s56
	v_pk_mul_f32 v[70:71], v[162:163], v[184:185] op_sel_hi:[0,1]
	s_addc_u32 s5, s70, s35
	v_pk_mul_f32 v[72:73], v[162:163], v[180:181] op_sel_hi:[0,1]
	s_waitcnt lgkmcnt(0)
	v_pk_mul_f32 v[68:69], v[70:71], v[246:247]
	v_lshl_add_u64 v[70:71], s[4:5], 0, v[114:115]
	v_add_co_u32_e32 v70, vcc, s1, v70
	v_pk_mul_f32 v[66:67], v[72:73], v[244:245]
	s_nop 0
	v_addc_co_u32_e32 v71, vcc, 0, v71, vcc
	global_store_dwordx4 v[70:71], v[66:69], off offset:16
	s_or_b32 s4, s31, 1
	s_mul_hi_i32 s5, s4, 0x1c000
	s_mul_i32 s4, s4, 0x1c000
	s_add_u32 s4, s69, s4
	v_pk_mul_f32 v[70:71], v[162:163], v[182:183] op_sel:[1,0]
	s_addc_u32 s5, s70, s5
	v_pk_mul_f32 v[72:73], v[162:163], v[178:179] op_sel:[1,0]
	v_pk_mul_f32 v[68:69], v[70:71], v[246:247]
	v_lshl_add_u64 v[70:71], s[4:5], 0, v[114:115]
	v_add_co_u32_e32 v70, vcc, 0xe000, v70
	v_pk_mul_f32 v[66:67], v[72:73], v[244:245]
	s_nop 0
	v_addc_co_u32_e32 v71, vcc, 0, v71, vcc
	global_store_dwordx4 v[70:71], v[66:69], off offset:16
.LBB0_1386:
	s_or_b64 exec, exec, s[18:19]
	s_waitcnt lgkmcnt(0)
	v_fmamk_f32 v66, v130, 0x39800000, v237
	v_rsq_f32_e32 v66, v66
	v_fmamk_f32 v67, v131, 0x39800000, v237
	v_rsq_f32_e32 v67, v67
	v_fmamk_f32 v68, v132, 0x39800000, v237
	v_pk_mul_f32 v[130:131], v[134:135], v[66:67]
	v_cvt_f32_i32_e32 v135, v63
	v_cvt_f32_i32_e32 v134, v62
	v_cndmask_b32_e64 v66, 0, 1, s[12:13]
	v_rsq_f32_e32 v68, v68
	v_fmamk_f32 v69, v133, 0x39800000, v237
	v_cmp_ne_u32_e64 s[4:5], 1, v66
	v_rsq_f32_e32 v69, v69
	s_nop 0
	v_pk_mul_f32 v[132:133], v[136:137], v[68:69]
	v_cvt_f32_i32_e32 v137, v65
	v_cvt_f32_i32_e32 v136, v64
	s_and_saveexec_b64 s[18:19], s[6:7]
	s_cbranch_execz .LBB0_1403
	v_add_lshl_u32 v66, s47, v106, 4
	v_add_u32_e32 v68, 0, v66
	v_mov_b32_e32 v67, v132
	v_pk_mul_f32 v[64:65], v[132:133], v[136:137] op_sel_hi:[0,1]
	v_pk_mul_f32 v[62:63], v[132:133], v[134:135] op_sel_hi:[0,1]
	v_add_u32_e32 v68, 0x20c00, v68
	s_and_b64 vcc, exec, s[4:5]
	ds_write_b128 v68, v[62:65]
	s_cbranch_vccnz .LBB0_1389
	s_lshl_b64 s[6:7], s[42:43], 2
	s_add_u32 s6, s94, s6
	s_addc_u32 s7, s95, s7
	v_lshl_add_u64 v[68:69], v[204:205], 2, s[6:7]
	ds_read_b128 v[248:251], v252 offset:4096
	s_add_u32 s6, s71, s56
	s_addc_u32 s7, s72, s35
	s_waitcnt lgkmcnt(0)
	v_pk_mul_f32 v[64:65], v[64:65], v[250:251]
	v_pk_mul_f32 v[62:63], v[62:63], v[248:249]
	v_lshl_add_u64 v[68:69], v[186:187], 2, s[6:7]
	global_store_dwordx4 v[68:69], v[62:65], off

.LBB0_1393:
	s_andn2_b64 vcc, exec, s[6:7]
	s_cbranch_vccnz .LBB0_1395
	s_lshl_b64 s[6:7], s[42:43], 2
	s_add_u32 s6, s94, s6
	s_addc_u32 s7, s95, s7
	v_lshl_add_u64 v[76:77], v[204:205], 2, s[6:7]
	ds_read_b128 v[248:251], v252 offset:4112
	s_add_u32 s6, s71, s56
	s_addc_u32 s7, s72, s35
	s_waitcnt lgkmcnt(0)
	v_pk_mul_f32 v[64:65], v[64:65], v[250:251]
	v_pk_mul_f32 v[62:63], v[62:63], v[248:249]
	v_lshl_add_u64 v[72:73], s[6:7], 0, v[114:115]
	global_store_dwordx4 v[72:73], v[62:65], off offset:16
	v_mov_b32_e32 v72, v133
	v_mov_b32_e32 v73, v133
	v_cvt_f32_i32_e32 v63, v27
	v_cvt_f32_i32_e32 v62, v26
	v_cvt_f32_i32_e32 v65, v29
	v_cvt_f32_i32_e32 v64, v28
	s_or_b32 s6, s31, 1
	v_pk_mul_f32 v[62:63], v[68:69], v[62:63]
	s_mul_hi_i32 s7, s6, 0x1c000
	v_pk_mul_f32 v[64:65], v[72:73], v[64:65]
	ds_write_b128 v70, v[62:65] offset:16
	s_mul_i32 s6, s6, 0x1c000
	s_add_u32 s6, s71, s6
	s_addc_u32 s7, s72, s7
	v_pk_mul_f32 v[64:65], v[64:65], v[250:251]
	v_pk_mul_f32 v[62:63], v[62:63], v[248:249]
	v_lshl_add_u64 v[70:71], s[6:7], 0, v[114:115]
	global_store_dwordx4 v[70:71], v[62:65], off offset:16

.LBB0_1397:
	s_andn2_b64 vcc, exec, s[6:7]
	s_cbranch_vccnz .LBB0_1399
	s_lshl_b64 s[6:7], s[42:43], 2
	s_add_u32 s6, s94, s6
	s_addc_u32 s7, s95, s7
	v_lshl_add_u64 v[76:77], v[204:205], 2, s[6:7]
	ds_read_b128 v[248:251], v252 offset:4608
	s_add_u32 s6, s71, s56
	s_addc_u32 s7, s72, s35
	s_waitcnt lgkmcnt(0)
	v_pk_mul_f32 v[62:63], v[62:63], v[248:249]
	v_lshl_add_u64 v[72:73], s[6:7], 0, v[114:115]
	v_add_co_u32_e32 v72, vcc, s1, v72
	v_pk_mul_f32 v[64:65], v[64:65], v[250:251]
	s_nop 0
	v_addc_co_u32_e32 v73, vcc, 0, v73, vcc
	global_store_dwordx4 v[72:73], v[62:65], off
	v_mov_b32_e32 v72, v133
	v_mov_b32_e32 v73, v133
	v_cvt_f32_i32_e32 v63, v35
	v_cvt_f32_i32_e32 v62, v34
	v_cvt_f32_i32_e32 v65, v37
	v_cvt_f32_i32_e32 v64, v36
	s_or_b32 s6, s31, 1
	v_pk_mul_f32 v[62:63], v[68:69], v[62:63]
	s_mul_hi_i32 s7, s6, 0x1c000
	v_pk_mul_f32 v[64:65], v[72:73], v[64:65]
	ds_write_b128 v70, v[62:65] offset:16
	s_mul_i32 s6, s6, 0x1c000
	s_add_u32 s6, s71, s6
	s_addc_u32 s7, s72, s7
	v_pk_mul_f32 v[62:63], v[62:63], v[248:249]
	v_lshl_add_u64 v[70:71], s[6:7], 0, v[114:115]
	v_add_co_u32_e32 v70, vcc, 0xe000, v70
	v_pk_mul_f32 v[64:65], v[64:65], v[250:251]
	s_nop 0
	v_addc_co_u32_e32 v71, vcc, 0, v71, vcc
	global_store_dwordx4 v[70:71], v[62:65], off

.LBB0_1401:
	s_andn2_b64 vcc, exec, s[6:7]
	s_cbranch_vccnz .LBB0_1403
	s_lshl_b64 s[6:7], s[42:43], 2
	s_add_u32 s6, s94, s6
	s_addc_u32 s7, s95, s7
	v_lshl_add_u64 v[74:75], v[204:205], 2, s[6:7]
	ds_read_b128 v[248:251], v252 offset:4624
	s_add_u32 s6, s71, s56
	s_addc_u32 s7, s72, s35
	s_waitcnt lgkmcnt(0)
	v_pk_mul_f32 v[62:63], v[62:63], v[248:249]
	v_lshl_add_u64 v[70:71], s[6:7], 0, v[114:115]
	v_add_co_u32_e32 v70, vcc, s1, v70
	v_pk_mul_f32 v[64:65], v[64:65], v[250:251]
	s_nop 0
	v_addc_co_u32_e32 v71, vcc, 0, v71, vcc
	global_store_dwordx4 v[70:71], v[62:65], off offset:16
	v_mov_b32_e32 v70, v133
	v_mov_b32_e32 v71, v133
	v_cvt_f32_i32_e32 v63, v3
	v_cvt_f32_i32_e32 v62, v2
	v_cvt_f32_i32_e32 v65, v5
	v_cvt_f32_i32_e32 v64, v4
	s_or_b32 s6, s31, 1
	v_pk_mul_f32 v[62:63], v[68:69], v[62:63]
	s_mul_hi_i32 s7, s6, 0x1c000
	v_pk_mul_f32 v[64:65], v[70:71], v[64:65]
	ds_write_b128 v66, v[62:65] offset:16
	s_mul_i32 s6, s6, 0x1c000
	s_add_u32 s6, s71, s6
	s_addc_u32 s7, s72, s7
	v_pk_mul_f32 v[62:63], v[62:63], v[248:249]
	v_lshl_add_u64 v[66:67], s[6:7], 0, v[114:115]
	v_add_co_u32_e32 v66, vcc, 0xe000, v66
	v_pk_mul_f32 v[64:65], v[64:65], v[250:251]
	s_nop 0
	v_addc_co_u32_e32 v67, vcc, 0, v67, vcc
	global_store_dwordx4 v[66:67], v[62:65], off offset:16

.LBB0_2061:
	s_or_b64 exec, exec, s[2:3]
	s_lshl_b32 s2, s40, 7
	v_lshlrev_b32_e32 v204, 3, v239
	s_or_b32 s2, s2, s62
	v_cvt_f32_i32_e32 v195, v119
	v_cvt_f32_i32_e32 v194, v118
	v_cvt_f32_i32_e32 v193, v121
	v_cvt_f32_i32_e32 v192, v120
	v_cvt_f32_i32_e32 v191, v115
	v_cvt_f32_i32_e32 v190, v114
	v_cvt_f32_i32_e32 v189, v117
	v_cvt_f32_i32_e32 v188, v116
	v_add_u32_e32 v186, s2, v204
	s_lshl_b32 s40, s40, 8
	s_lshl_b32 s31, s38, 1
	v_ashrrev_i32_e32 v187, 31, v186
	v_or_b32_e32 v122, s39, v222
	s_ashr_i32 s41, s40, 31
	v_ashrrev_i32_e32 v205, 31, v204
	v_cmp_eq_u32_e64 s[2:3], 0, v122
	s_mul_hi_i32 s42, s31, 0x1c000
	s_mul_i32 s43, s31, 0x1c000
	v_lshlrev_b64 v[114:115], 2, v[186:187]
	s_mul_i32 vcc_lo, s29, 0x1400
	v_add_u32_e32 v252, s62, v204
	v_lshl_add_u32 v252, v252, 2, vcc_lo
	v_add_u32_e32 v252, 0x22c00, v252
	s_and_saveexec_b64 s[18:19], s[2:3]
	s_cbranch_execz .LBB0_2063
	s_lshl_b64 s[90:91], s[40:41], 2
	s_add_u32 s90, s79, s90
	s_addc_u32 s91, s80, s91
	v_lshl_add_u64 v[124:125], v[204:205], 2, s[90:91]
	ds_read_b128 v[244:247], v252 offset:4096
	s_add_u32 s90, s55, s43
	v_pk_mul_f32 v[120:121], v[162:163], v[192:193] op_sel_hi:[0,1]
	v_pk_mul_f32 v[122:123], v[162:163], v[194:195] op_sel_hi:[0,1]
	s_addc_u32 s91, s56, s42
	s_or_b32 s87, s31, 1
	s_waitcnt lgkmcnt(0)
	v_pk_mul_f32 v[116:117], v[122:123], v[244:245]
	v_pk_mul_f32 v[118:119], v[120:121], v[246:247]
	v_lshl_add_u64 v[120:121], s[90:91], 0, v[114:115]
	global_store_dwordx4 v[120:121], v[116:119], off
	s_mul_hi_i32 s91, s87, 0x1c000
	s_mul_i32 s87, s87, 0x1c000
	s_add_u32 s90, s55, s87
	v_pk_mul_f32 v[120:121], v[162:163], v[188:189] op_sel:[1,0]
	v_pk_mul_f32 v[122:123], v[162:163], v[190:191] op_sel:[1,0]
	s_addc_u32 s91, s56, s91
	v_pk_mul_f32 v[116:117], v[122:123], v[244:245]
	v_pk_mul_f32 v[118:119], v[120:121], v[246:247]
	v_lshl_add_u64 v[120:121], s[90:91], 0, v[114:115]
	global_store_dwordx4 v[120:121], v[116:119], off

.LBB0_2065:
	s_or_b64 exec, exec, s[18:19]
	v_cvt_f32_i32_e32 v121, v103
	v_cvt_f32_i32_e32 v120, v102
	v_cvt_f32_i32_e32 v125, v105
	v_cvt_f32_i32_e32 v124, v104
	v_cvt_f32_i32_e32 v119, v99
	v_cvt_f32_i32_e32 v118, v98
	v_cvt_f32_i32_e32 v123, v101
	v_cvt_f32_i32_e32 v122, v100
	s_and_saveexec_b64 s[18:19], s[2:3]
	s_cbranch_execz .LBB0_2067
	s_lshl_b64 s[90:91], s[40:41], 2
	s_add_u32 s90, s79, s90
	s_addc_u32 s91, s80, s91
	v_lshl_add_u64 v[108:109], v[204:205], 2, s[90:91]
	ds_read_b128 v[244:247], v252 offset:4112
	s_add_u32 s90, s55, s43
	v_pk_mul_f32 v[102:103], v[162:163], v[124:125] op_sel_hi:[0,1]
	v_pk_mul_f32 v[104:105], v[162:163], v[120:121] op_sel_hi:[0,1]
	s_addc_u32 s91, s56, s42
	s_or_b32 s87, s31, 1
	s_waitcnt lgkmcnt(0)
	v_pk_mul_f32 v[98:99], v[104:105], v[244:245]
	v_pk_mul_f32 v[100:101], v[102:103], v[246:247]
	v_lshl_add_u64 v[102:103], s[90:91], 0, v[114:115]
	global_store_dwordx4 v[102:103], v[98:101], off offset:16
	s_mul_hi_i32 s91, s87, 0x1c000
	s_mul_i32 s87, s87, 0x1c000
	s_add_u32 s90, s55, s87
	v_pk_mul_f32 v[102:103], v[162:163], v[122:123] op_sel:[1,0]
	v_pk_mul_f32 v[104:105], v[162:163], v[118:119] op_sel:[1,0]
	s_addc_u32 s91, s56, s91
	v_pk_mul_f32 v[98:99], v[104:105], v[244:245]
	v_pk_mul_f32 v[100:101], v[102:103], v[246:247]
	v_lshl_add_u64 v[102:103], s[90:91], 0, v[114:115]
	global_store_dwordx4 v[102:103], v[98:101], off offset:16

.LBB0_2069:
	s_or_b64 exec, exec, s[18:19]
	v_cvt_f32_i32_e32 v221, v87
	v_cvt_f32_i32_e32 v220, v86
	v_cvt_f32_i32_e32 v219, v89
	v_cvt_f32_i32_e32 v218, v88
	v_cvt_f32_i32_e32 v217, v83
	v_cvt_f32_i32_e32 v216, v82
	v_cvt_f32_i32_e32 v215, v85
	v_cvt_f32_i32_e32 v214, v84
	s_and_saveexec_b64 s[18:19], s[2:3]
	s_cbranch_execz .LBB0_2071
	s_lshl_b64 s[90:91], s[40:41], 2
	s_add_u32 s90, s79, s90
	s_addc_u32 s91, s80, s91
	v_lshl_add_u64 v[90:91], v[204:205], 2, s[90:91]
	ds_read_b128 v[244:247], v252 offset:4608
	s_add_u32 s90, s55, s43
	v_pk_mul_f32 v[86:87], v[162:163], v[218:219] op_sel_hi:[0,1]
	s_addc_u32 s91, s56, s42
	v_pk_mul_f32 v[88:89], v[162:163], v[220:221] op_sel_hi:[0,1]
	s_or_b32 s87, s31, 1
	s_waitcnt lgkmcnt(0)
	v_pk_mul_f32 v[84:85], v[86:87], v[246:247]
	v_lshl_add_u64 v[86:87], s[90:91], 0, v[114:115]
	v_add_co_u32_e32 v86, vcc, s17, v86
	v_pk_mul_f32 v[82:83], v[88:89], v[244:245]
	s_nop 0
	v_addc_co_u32_e32 v87, vcc, 0, v87, vcc
	global_store_dwordx4 v[86:87], v[82:85], off
	s_mul_hi_i32 s91, s87, 0x1c000
	s_mul_i32 s87, s87, 0x1c000
	s_add_u32 s90, s55, s87
	v_pk_mul_f32 v[86:87], v[162:163], v[214:215] op_sel:[1,0]
	s_addc_u32 s91, s56, s91
	v_pk_mul_f32 v[88:89], v[162:163], v[216:217] op_sel:[1,0]
	v_pk_mul_f32 v[84:85], v[86:87], v[246:247]
	v_lshl_add_u64 v[86:87], s[90:91], 0, v[114:115]
	v_add_co_u32_e32 v86, vcc, 0xe000, v86
	v_pk_mul_f32 v[82:83], v[88:89], v[244:245]
	s_nop 0
	v_addc_co_u32_e32 v87, vcc, 0, v87, vcc
	global_store_dwordx4 v[86:87], v[82:85], off

.LBB0_2073:
	s_or_b64 exec, exec, s[18:19]
	v_cvt_f32_i32_e32 v181, v71
	v_cvt_f32_i32_e32 v180, v70
	v_cvt_f32_i32_e32 v185, v73
	v_cvt_f32_i32_e32 v184, v72
	v_cvt_f32_i32_e32 v179, v67
	v_cvt_f32_i32_e32 v178, v66
	v_cvt_f32_i32_e32 v183, v69
	v_cvt_f32_i32_e32 v182, v68
	s_and_saveexec_b64 s[18:19], s[2:3]
	s_cbranch_execz .LBB0_2075
	s_lshl_b64 s[2:3], s[40:41], 2
	s_add_u32 s2, s79, s2
	s_addc_u32 s3, s80, s3
	v_lshl_add_u64 v[74:75], v[204:205], 2, s[2:3]
	ds_read_b128 v[244:247], v252 offset:4624
	s_add_u32 s2, s55, s43
	v_pk_mul_f32 v[70:71], v[162:163], v[184:185] op_sel_hi:[0,1]
	s_addc_u32 s3, s56, s42
	v_pk_mul_f32 v[72:73], v[162:163], v[180:181] op_sel_hi:[0,1]
	s_waitcnt lgkmcnt(0)
	v_pk_mul_f32 v[68:69], v[70:71], v[246:247]
	v_lshl_add_u64 v[70:71], s[2:3], 0, v[114:115]
	v_add_co_u32_e32 v70, vcc, s17, v70
	v_pk_mul_f32 v[66:67], v[72:73], v[244:245]
	s_nop 0
	v_addc_co_u32_e32 v71, vcc, 0, v71, vcc
	global_store_dwordx4 v[70:71], v[66:69], off offset:16
	s_or_b32 s2, s31, 1
	s_mul_hi_i32 s3, s2, 0x1c000
	s_mul_i32 s2, s2, 0x1c000
	s_add_u32 s2, s55, s2
	v_pk_mul_f32 v[70:71], v[162:163], v[182:183] op_sel:[1,0]
	s_addc_u32 s3, s56, s3
	v_pk_mul_f32 v[72:73], v[162:163], v[178:179] op_sel:[1,0]
	v_pk_mul_f32 v[68:69], v[70:71], v[246:247]
	v_lshl_add_u64 v[70:71], s[2:3], 0, v[114:115]
	v_add_co_u32_e32 v70, vcc, 0xe000, v70
	v_pk_mul_f32 v[66:67], v[72:73], v[244:245]
	s_nop 0
	v_addc_co_u32_e32 v71, vcc, 0, v71, vcc
	global_store_dwordx4 v[70:71], v[66:69], off offset:16
.LBB0_2075:
	s_or_b64 exec, exec, s[18:19]
	s_waitcnt lgkmcnt(0)
	v_fmamk_f32 v66, v130, 0x39800000, v237
	v_rsq_f32_e32 v66, v66
	v_fmamk_f32 v67, v131, 0x39800000, v237
	v_rsq_f32_e32 v67, v67
	v_fmamk_f32 v68, v132, 0x39800000, v237
	v_pk_mul_f32 v[130:131], v[134:135], v[66:67]
	v_cvt_f32_i32_e32 v135, v63
	v_cvt_f32_i32_e32 v134, v62
	v_cndmask_b32_e64 v66, 0, 1, s[10:11]
	v_rsq_f32_e32 v68, v68
	v_fmamk_f32 v69, v133, 0x39800000, v237
	v_cmp_ne_u32_e64 s[2:3], 1, v66
	v_rsq_f32_e32 v69, v69
	s_nop 0
	v_pk_mul_f32 v[132:133], v[136:137], v[68:69]
	v_cvt_f32_i32_e32 v137, v65
	v_cvt_f32_i32_e32 v136, v64
	s_and_saveexec_b64 s[18:19], s[4:5]
	s_cbranch_execz .LBB0_2092
	v_add_lshl_u32 v66, s68, v106, 4
	v_add_u32_e32 v68, 0, v66
	v_mov_b32_e32 v67, v132
	v_pk_mul_f32 v[64:65], v[132:133], v[136:137] op_sel_hi:[0,1]
	v_pk_mul_f32 v[62:63], v[132:133], v[134:135] op_sel_hi:[0,1]
	v_add_u32_e32 v68, 0x20c00, v68
	s_and_b64 vcc, exec, s[2:3]
	ds_write_b128 v68, v[62:65]
	s_cbranch_vccnz .LBB0_2078
	s_lshl_b64 s[4:5], s[40:41], 2
	s_add_u32 s4, s79, s4
	s_addc_u32 s5, s80, s5
	v_lshl_add_u64 v[68:69], v[204:205], 2, s[4:5]
	ds_read_b128 v[248:251], v252 offset:4096
	s_add_u32 s4, s57, s43
	s_addc_u32 s5, s60, s42
	s_waitcnt lgkmcnt(0)
	v_pk_mul_f32 v[64:65], v[64:65], v[250:251]
	v_pk_mul_f32 v[62:63], v[62:63], v[248:249]
	v_lshl_add_u64 v[68:69], v[186:187], 2, s[4:5]
	global_store_dwordx4 v[68:69], v[62:65], off

.LBB0_2082:
	s_andn2_b64 vcc, exec, s[4:5]
	s_cbranch_vccnz .LBB0_2084
	s_lshl_b64 s[4:5], s[40:41], 2
	s_add_u32 s4, s79, s4
	s_addc_u32 s5, s80, s5
	v_lshl_add_u64 v[76:77], v[204:205], 2, s[4:5]
	ds_read_b128 v[248:251], v252 offset:4112
	s_add_u32 s4, s57, s43
	s_addc_u32 s5, s60, s42
	s_waitcnt lgkmcnt(0)
	v_pk_mul_f32 v[64:65], v[64:65], v[250:251]
	v_pk_mul_f32 v[62:63], v[62:63], v[248:249]
	v_lshl_add_u64 v[72:73], s[4:5], 0, v[114:115]
	global_store_dwordx4 v[72:73], v[62:65], off offset:16
	v_mov_b32_e32 v72, v133
	v_mov_b32_e32 v73, v133
	v_cvt_f32_i32_e32 v63, v27
	v_cvt_f32_i32_e32 v62, v26
	v_cvt_f32_i32_e32 v65, v29
	v_cvt_f32_i32_e32 v64, v28
	s_or_b32 s4, s31, 1
	v_pk_mul_f32 v[62:63], v[68:69], v[62:63]
	s_mul_hi_i32 s5, s4, 0x1c000
	v_pk_mul_f32 v[64:65], v[72:73], v[64:65]
	ds_write_b128 v70, v[62:65] offset:16
	s_mul_i32 s4, s4, 0x1c000
	s_add_u32 s4, s57, s4
	s_addc_u32 s5, s60, s5
	v_pk_mul_f32 v[64:65], v[64:65], v[250:251]
	v_pk_mul_f32 v[62:63], v[62:63], v[248:249]
	v_lshl_add_u64 v[70:71], s[4:5], 0, v[114:115]
	global_store_dwordx4 v[70:71], v[62:65], off offset:16

.LBB0_2086:
	s_andn2_b64 vcc, exec, s[4:5]
	s_cbranch_vccnz .LBB0_2088
	s_lshl_b64 s[4:5], s[40:41], 2
	s_add_u32 s4, s79, s4
	s_addc_u32 s5, s80, s5
	v_lshl_add_u64 v[76:77], v[204:205], 2, s[4:5]
	ds_read_b128 v[248:251], v252 offset:4608
	s_add_u32 s4, s57, s43
	s_addc_u32 s5, s60, s42
	s_waitcnt lgkmcnt(0)
	v_pk_mul_f32 v[62:63], v[62:63], v[248:249]
	v_lshl_add_u64 v[72:73], s[4:5], 0, v[114:115]
	v_add_co_u32_e32 v72, vcc, s17, v72
	v_pk_mul_f32 v[64:65], v[64:65], v[250:251]
	s_nop 0
	v_addc_co_u32_e32 v73, vcc, 0, v73, vcc
	global_store_dwordx4 v[72:73], v[62:65], off
	v_mov_b32_e32 v72, v133
	v_mov_b32_e32 v73, v133
	v_cvt_f32_i32_e32 v63, v35
	v_cvt_f32_i32_e32 v62, v34
	v_cvt_f32_i32_e32 v65, v37
	v_cvt_f32_i32_e32 v64, v36
	s_or_b32 s4, s31, 1
	v_pk_mul_f32 v[62:63], v[68:69], v[62:63]
	s_mul_hi_i32 s5, s4, 0x1c000
	v_pk_mul_f32 v[64:65], v[72:73], v[64:65]
	ds_write_b128 v70, v[62:65] offset:16
	s_mul_i32 s4, s4, 0x1c000
	s_add_u32 s4, s57, s4
	s_addc_u32 s5, s60, s5
	v_pk_mul_f32 v[62:63], v[62:63], v[248:249]
	v_lshl_add_u64 v[70:71], s[4:5], 0, v[114:115]
	v_add_co_u32_e32 v70, vcc, 0xe000, v70
	v_pk_mul_f32 v[64:65], v[64:65], v[250:251]
	s_nop 0
	v_addc_co_u32_e32 v71, vcc, 0, v71, vcc
	global_store_dwordx4 v[70:71], v[62:65], off

.LBB0_2090:
	s_andn2_b64 vcc, exec, s[4:5]
	s_cbranch_vccnz .LBB0_2092
	s_lshl_b64 s[4:5], s[40:41], 2
	s_add_u32 s4, s79, s4
	s_addc_u32 s5, s80, s5
	v_lshl_add_u64 v[74:75], v[204:205], 2, s[4:5]
	ds_read_b128 v[248:251], v252 offset:4624
	s_add_u32 s4, s57, s43
	s_addc_u32 s5, s60, s42
	s_waitcnt lgkmcnt(0)
	v_pk_mul_f32 v[62:63], v[62:63], v[248:249]
	v_lshl_add_u64 v[70:71], s[4:5], 0, v[114:115]
	v_add_co_u32_e32 v70, vcc, s17, v70
	v_pk_mul_f32 v[64:65], v[64:65], v[250:251]
	s_nop 0
	v_addc_co_u32_e32 v71, vcc, 0, v71, vcc
	global_store_dwordx4 v[70:71], v[62:65], off offset:16
	v_mov_b32_e32 v70, v133
	v_mov_b32_e32 v71, v133
	v_cvt_f32_i32_e32 v63, v3
	v_cvt_f32_i32_e32 v62, v2
	v_cvt_f32_i32_e32 v65, v5
	v_cvt_f32_i32_e32 v64, v4
	s_or_b32 s4, s31, 1
	v_pk_mul_f32 v[62:63], v[68:69], v[62:63]
	s_mul_hi_i32 s5, s4, 0x1c000
	v_pk_mul_f32 v[64:65], v[70:71], v[64:65]
	ds_write_b128 v66, v[62:65] offset:16
	s_mul_i32 s4, s4, 0x1c000
	s_add_u32 s4, s57, s4
	s_addc_u32 s5, s60, s5
	v_pk_mul_f32 v[62:63], v[62:63], v[248:249]
	v_lshl_add_u64 v[66:67], s[4:5], 0, v[114:115]
	v_add_co_u32_e32 v66, vcc, 0xe000, v66
	v_pk_mul_f32 v[64:65], v[64:65], v[250:251]
	s_nop 0
	v_addc_co_u32_e32 v67, vcc, 0, v67, vcc
	global_store_dwordx4 v[66:67], v[62:65], off offset:16
